# P3 merge loop: the three OG loads of an iteration issued together with the LSE loads (before the weights are computed), LSE wait relaxed to vmcnt(3)
# speedup vs baseline: 1.0014x; 1.0004x over previous
.LBB0_426:
	v_lshrrev_b64 v[2:3], 7, v[66:67]
	v_lshlrev_b64 v[4:5], 5, v[2:3]
	v_lshrrev_b32_e32 v0, 5, v6
	v_lshl_add_u64 v[4:5], s[14:15], 0, v[4:5]
	v_and_b32_e32 v0, 28, v0
	v_lshl_add_u64 v[4:5], v[4:5], 0, v[0:1]
	v_or_b32_e32 v8, 0x2000, v2
	v_mov_b32_e32 v9, v3
	global_load_dword v10, v[4:5], off
	v_lshlrev_b64 v[4:5], 5, v[8:9]
	v_lshl_add_u64 v[4:5], s[14:15], 0, v[4:5]
	v_lshl_add_u64 v[4:5], v[4:5], 0, v[0:1]
	v_or_b32_e32 v12, 0x4000, v2
	v_mov_b32_e32 v13, v3
	global_load_dword v11, v[4:5], off
	v_lshlrev_b64 v[4:5], 5, v[12:13]
	v_lshl_add_u64 v[4:5], s[14:15], 0, v[4:5]
	v_lshl_add_u64 v[4:5], v[4:5], 0, v[0:1]
	global_load_dword v0, v[4:5], off
	v_and_b32_e32 v7, 0x3f8, v6
	v_lshlrev_b64 v[2:3], 11, v[2:3]
	v_lshlrev_b64 v[8:9], 11, v[8:9]
	v_lshl_add_u64 v[2:3], s[12:13], 0, v[2:3]
	v_lshl_add_u64 v[8:9], s[12:13], 0, v[8:9]
	v_lshlrev_b64 v[12:13], 11, v[12:13]
	v_lshl_add_u64 v[12:13], s[12:13], 0, v[12:13]
	s_mov_b64 s[22:23], 0xfffff
	v_add_u32_e32 v6, s61, v6
	v_lshlrev_b32_e32 v26, 1, v7
	v_mov_b32_e32 v27, v1
	v_lshl_add_u64 v[2:3], v[2:3], 0, v[26:27]
	global_load_dwordx4 v[40:43], v[2:3], off nt
	v_lshl_add_u64 v[8:9], v[8:9], 0, v[26:27]
	global_load_dwordx4 v[44:47], v[8:9], off nt
	v_lshl_add_u64 v[12:13], v[12:13], 0, v[26:27]
	global_load_dwordx4 v[48:51], v[12:13], off nt
	s_waitcnt vmcnt(3)
	v_max3_f32 v4, v10, v11, v0
	v_sub_f32_e32 v5, v10, v4
	v_mul_f32_e32 v5, 0x3fb8aa3b, v5
	v_exp_f32_e32 v17, v5
	v_sub_f32_e32 v5, v11, v4
	v_mul_f32_e32 v5, 0x3fb8aa3b, v5
	v_sub_f32_e32 v0, v0, v4
	v_exp_f32_e32 v16, v5
	v_mul_f32_e32 v0, 0x3fb8aa3b, v0
	v_exp_f32_e32 v19, v0
	v_add_f32_e32 v0, v17, v16
	v_add_f32_e32 v0, v19, v0
	v_div_scale_f32 v4, s[4:5], v0, v0, 1.0
	v_rcp_f32_e32 v5, v4
	s_nop 0
	v_fma_f32 v10, -v4, v5, 1.0
	v_fmac_f32_e32 v5, v10, v5
	v_div_scale_f32 v10, vcc, 1.0, v0, 1.0
	v_mul_f32_e32 v11, v10, v5
	v_fma_f32 v14, -v4, v11, v10
	v_fmac_f32_e32 v11, v14, v5
	v_fma_f32 v4, -v4, v11, v10
	v_div_fmas_f32 v4, v4, v5, v11
	v_div_fixup_f32 v18, v4, v0, 1.0
	v_lshlrev_b32_e32 v0, 1, v7
	v_pk_mul_f32 v[16:17], v[16:17], v[18:19] op_sel_hi:[1,0]
	v_mul_f32_e32 v20, v19, v18
	v_alignbit_b32 v7, v67, v66, 7
	s_waitcnt vmcnt(2)
	v_lshlrev_b32_e32 v22, 16, v40
	v_and_b32_e32 v19, 0xffff0000, v40
	s_waitcnt vmcnt(1)
	v_and_b32_e32 v23, 0xffff0000, v44
	v_lshlrev_b32_e32 v18, 16, v44
	v_pk_mul_f32 v[22:23], v[16:17], v[22:23] op_sel:[1,0] op_sel_hi:[0,1]
	s_waitcnt vmcnt(0)
	v_lshlrev_b32_e32 v24, 16, v48
	v_and_b32_e32 v25, 0xffff0000, v48
	v_pk_fma_f32 v[18:19], v[16:17], v[18:19], v[22:23]
	v_lshlrev_b32_e32 v8, 16, v41
	v_pk_fma_f32 v[18:19], v[20:21], v[24:25], v[18:19] op_sel_hi:[0,1,1]
	v_cvt_pk_bf16_f32 v2, v18, v19
	v_lshlrev_b32_e32 v18, 16, v45
	v_and_b32_e32 v9, 0xffff0000, v45
	v_and_b32_e32 v19, 0xffff0000, v41
	v_pk_mul_f32 v[8:9], v[16:17], v[8:9] op_sel:[1,0] op_sel_hi:[0,1]
	v_lshlrev_b32_e32 v12, 16, v49
	v_and_b32_e32 v13, 0xffff0000, v49
	v_pk_fma_f32 v[8:9], v[16:17], v[18:19], v[8:9]
	v_lshlrev_b32_e32 v18, 16, v50
	v_pk_fma_f32 v[8:9], v[20:21], v[12:13], v[8:9] op_sel_hi:[0,1,1]
	v_lshlrev_b32_e32 v12, 16, v42
	v_and_b32_e32 v13, 0xffff0000, v46
	v_cvt_pk_bf16_f32 v3, v8, v9
	v_lshlrev_b32_e32 v8, 16, v46
	v_and_b32_e32 v9, 0xffff0000, v42
	v_pk_mul_f32 v[12:13], v[16:17], v[12:13] op_sel:[1,0] op_sel_hi:[0,1]
	v_and_b32_e32 v19, 0xffff0000, v50
	v_pk_fma_f32 v[8:9], v[16:17], v[8:9], v[12:13]
	v_lshlrev_b32_e32 v10, 16, v43
	v_pk_fma_f32 v[8:9], v[20:21], v[18:19], v[8:9] op_sel_hi:[0,1,1]
	v_cvt_pk_bf16_f32 v4, v8, v9
	v_lshlrev_b32_e32 v8, 16, v47
	v_and_b32_e32 v11, 0xffff0000, v47
	v_and_b32_e32 v9, 0xffff0000, v43
	v_pk_mul_f32 v[10:11], v[16:17], v[10:11] op_sel:[1,0] op_sel_hi:[0,1]
	v_pk_fma_f32 v[8:9], v[16:17], v[8:9], v[10:11]
	v_lshlrev_b32_e32 v10, 16, v51
	v_and_b32_e32 v11, 0xffff0000, v51
	v_pk_fma_f32 v[8:9], v[20:21], v[10:11], v[8:9] op_sel_hi:[0,1,1]
	v_cvt_pk_bf16_f32 v5, v8, v9
	v_mov_b64_e32 v[8:9], s[16:17]
	v_mad_u64_u32 v[8:9], s[4:5], v7, s18, v[8:9]
	v_mov_b32_e32 v10, v9
	v_lshrrev_b32_e32 v7, 7, v67
	v_mad_u64_u32 v[10:11], s[4:5], v7, s18, v[10:11]
	v_lshl_add_u64 v[66:67], v[66:67], 0, s[8:9]
	v_mov_b32_e32 v9, v10
	v_cmp_lt_u64_e32 vcc, s[22:23], v[66:67]
	v_lshl_add_u64 v[8:9], v[8:9], 0, v[0:1]
	s_or_b64 s[20:21], vcc, s[20:21]
	global_store_dwordx4 v[8:9], v[2:5], off
	s_andn2_b64 exec, exec, s[20:21]
	s_cbranch_execnz .LBB0_426
